# P5: residual tile x streamed via LDS-DMA to a dummy LDS slot during the K loop (2 x 1KB rows per wave per super-iteration), K-loop waits vmcnt(9)
# baseline (speedup 1.0000x reference)
; #define PG8_STAGE(bufoff, gbase, voff) do { _Pragma("unroll") for (int _i = 0; _i < 2; ++_i) \
;         __builtin_amdgcn_global_load_lds((const unsigned*)((const char*)(gbase) + (voff)[_i]), (PG8_LAS unsigned*)(lds + (bufoff) + ldsw + _i * 8192), 16, 0, 0); } while (0)
; #define PG8_LDA(dst, b, h) do { _Pragma("unroll") for (int m = 0; m < 4; ++m) _Pragma("unroll") for (int k = 0; k < 2; ++k) dst[m][k] = *(const PG8_LAS bf16x8*)(lds + PG8_SA(b, h) + aoff + m * 2048 + k * 1024); } while (0)
; #define PG8_LDB(dst, b, h) do { _Pragma("unroll") for (int n = 0; n < 2; ++n) _Pragma("unroll") for (int k = 0; k < 2; ++k) dst[n][k] = *(const PG8_LAS bf16x8*)(lds + PG8_SB(b, h) + boff + n * 2048 + k * 1024); } while (0)
; template <class Epi, class Sched, bool ALIGN_EPI = false, bool SP2 = false>
; __device__ __forceinline__ void gemm_phase(PG8_LAS unsigned char* lds, const Gemm g, const Sched& S, const Epi& E) {
;     ...
;         for (int t = 0; t < nt; t += 2) {
;             const bool last = (t == nt - 2);
;             const char* a1 = cA + (size_t)(t + 1) * kstep;
;             const char* a2 = last ? nA : cA + (size_t)(t + 2) * kstep; const char* b2 = last ? nB : cB + (size_t)(t + 2) * kstep;
;             const char* a3 = a2 + kstep; const char* b3 = b2 + kstep;
;             if (last && has_next) S.a_ready(nxt);
;             if constexpr (SP2) {
;             PG8_LDB(B0, 0, 0); PG8_LDB(B1, 0, 1); PG8_SCHED; PG8_LDA(At, 0, 0); PG8_STAGE(PG8_SA(1, 1), a1 + hstep, voffA);
;             PG8_WAIT_V(8); PG8_WAIT_L(0); PG8_BAR; PG8_MMA(0, 0, At, B0); PG8_MMA(0, 1, At, B1); PG8_BAR; PG8_SCHED;
;             PG8_LDA(At, 0, 1); PG8_STAGE(PG8_SB(0, 0), b2, voffB); PG8_STAGE(PG8_SB(0, 1), b2 + hstep, voffB); PG8_STAGE(PG8_SA(0, 0), a2, voffA);
;             PG8_WAIT_V(8); PG8_WAIT_L(0); PG8_BAR; PG8_MMA(1, 0, At, B0); PG8_MMA(1, 1, At, B1); PG8_BAR; PG8_SCHED;
;             PG8_LDB(B0, 1, 0); PG8_LDB(B1, 1, 1); PG8_SCHED; PG8_LDA(At, 1, 0); PG8_STAGE(PG8_SA(0, 1), a2 + hstep, voffA);
;             PG8_WAIT_V(8); PG8_WAIT_L(0); PG8_BAR; PG8_MMA(0, 0, At, B0); PG8_MMA(0, 1, At, B1); PG8_BAR; PG8_SCHED;
;             PG8_LDA(At, 1, 1); PG8_STAGE(PG8_SB(1, 0), b3, voffB); PG8_STAGE(PG8_SB(1, 1), b3 + hstep, voffB); PG8_STAGE(PG8_SA(1, 0), a3, voffA);
;             PG8_WAIT_V(8); PG8_WAIT_L(0); PG8_BAR; PG8_MMA(1, 0, At, B0); PG8_MMA(1, 1, At, B1); PG8_BAR; PG8_SCHED;
.LBB0_893:
	s_ashr_i32 s25, s24, 31
	s_lshl_b64 s[28:29], s[24:25], 20
	v_readlane_b32 s30, v236, 50
	v_readlane_b32 s31, v236, 51
	s_add_u32 s28, s30, s28
	s_addc_u32 s29, s31, s29
	s_and_b64 s[30:31], s[6:7], exec
	s_cselect_b32 s25, s29, s39
	s_cselect_b32 s35, s28, s38
	s_ashr_i32 s27, s26, 31
	s_lshl_b64 s[30:31], s[26:27], 20
	v_readlane_b32 s42, v236, 43
	v_readlane_b32 s43, v236, 44
	s_add_u32 s30, s42, s30
	s_addc_u32 s31, s43, s31
	s_and_b64 s[42:43], s[6:7], exec
	s_cselect_b32 s27, s31, s41
	s_cselect_b32 s55, s30, s40
	s_add_u32 s38, s38, 0x80080
	s_addc_u32 s39, s39, 0
	s_add_u32 s56, s40, 0x100
	s_addc_u32 s57, s41, 0
	s_mov_b32 s58, -2
	s_waitcnt lgkmcnt(0)
	v_readlane_b32 s98, v236, 7
	v_readlane_b32 s99, v236, 8
	v_lshrrev_b32_e32 v242, 6, v166
	v_lshlrev_b32_e32 v242, 7, v242
	v_and_b32_e32 v240, 0x60, v168
	v_add_u32_e32 v242, v242, v240
	v_lshl_add_u32 v242, s36, 8, v242
	v_lshlrev_b32_e32 v242, 13, v242
	v_and_b32_e32 v240, 15, v166
	v_and_b32_e32 v241, 12, v168
	v_lshl_add_u32 v240, v241, 2, v240
	v_lshl_add_u32 v242, v240, 4, v242
	s_lshl_b32 s100, s34, 10
	v_add_u32_e32 v240, s100, v242
	v_mov_b32_e32 v241, 0
	v_lshl_add_u64 v[240:241], s[98:99], 0, v[240:241]
	s_mov_b64 s[98:99], 0x2000
	v_readfirstlane_b32 s100, v166
	s_lshl_b32 s100, s100, 6
	v_readfirstlane_b32 s101, v168
	s_lshl_b32 s101, s101, 5
	s_add_i32 s100, s100, s101
	s_add_i32 s100, s100, 0x21000
	s_mov_b32 m0, s100
	s_nop 0
	global_load_lds_dwordx4 v[240:241], off
	v_lshl_add_u64 v[240:241], v[240:241], 0, s[98:99]
	ds_read_b128 v[72:75], v169
	ds_read_b128 v[84:87], v169 offset:1024
	ds_read_b128 v[92:95], v169 offset:2048
	ds_read_b128 v[96:99], v169 offset:3072
	ds_read_b128 v[156:159], v170
	ds_read_b128 v[160:163], v170 offset:1024
	ds_read_b128 v[174:177], v170 offset:2048
	ds_read_b128 v[178:181], v170 offset:3072
	s_add_u32 s40, s38, 0xfff80080
	s_addc_u32 s41, s39, -1
	s_cmp_eq_u32 s58, 28
	s_cselect_b32 s43, s25, s41
	s_cselect_b32 s42, s35, s40
	s_cselect_b32 s41, s27, s57
	s_cselect_b32 s40, s55, s56
	v_lshl_add_u64 v[164:165], s[38:39], 0, v[148:149]
	s_add_i32 m0, s37, 0xc000
	ds_read_b128 v[182:185], v171
	ds_read_b128 v[188:191], v171 offset:1024
	ds_read_b128 v[192:195], v171 offset:2048
	ds_read_b128 v[196:199], v171 offset:3072
	ds_read_b128 v[200:203], v171 offset:4096
	ds_read_b128 v[204:207], v171 offset:5120
	ds_read_b128 v[208:211], v171 offset:6144
	ds_read_b128 v[212:215], v171 offset:7168
	global_load_lds_dwordx4 v[164:165], off
	v_lshl_add_u64 v[164:165], s[38:39], 0, v[150:151]
	s_add_i32 m0, s37, 0xe000
	s_nop 0
	global_load_lds_dwordx4 v[164:165], off
	s_setprio 1
	s_waitcnt vmcnt(9)
	s_waitcnt lgkmcnt(0)
	s_barrier
	v_mfma_f32_16x16x32_bf16 v[140:143], v[72:75], v[182:185], 0
	v_mfma_f32_16x16x32_bf16 v[136:139], v[92:95], v[182:185], 0
	v_mfma_f32_16x16x32_bf16 v[124:127], v[72:75], v[192:195], 0
	v_mfma_f32_16x16x32_bf16 v[120:123], v[92:95], v[192:195], 0
	v_mfma_f32_16x16x32_bf16 v[108:111], v[72:75], v[200:203], 0
	v_mfma_f32_16x16x32_bf16 v[104:107], v[92:95], v[200:203], 0
	v_mfma_f32_16x16x32_bf16 v[80:83], v[72:75], v[208:211], 0
	v_mfma_f32_16x16x32_bf16 v[76:79], v[92:95], v[208:211], 0
	v_mfma_f32_16x16x32_bf16 v[140:143], v[84:87], v[188:191], v[140:143]
	v_mfma_f32_16x16x32_bf16 v[136:139], v[96:99], v[188:191], v[136:139]
	v_mfma_f32_16x16x32_bf16 v[124:127], v[84:87], v[196:199], v[124:127]
	v_mfma_f32_16x16x32_bf16 v[120:123], v[96:99], v[196:199], v[120:123]
	v_mfma_f32_16x16x32_bf16 v[108:111], v[84:87], v[204:207], v[108:111]
	v_mfma_f32_16x16x32_bf16 v[104:107], v[96:99], v[204:207], v[104:107]
	v_mfma_f32_16x16x32_bf16 v[80:83], v[84:87], v[212:215], v[80:83]
	v_mfma_f32_16x16x32_bf16 v[76:79], v[96:99], v[212:215], v[76:79]
	s_setprio 0
	s_setprio 1
	v_mfma_f32_16x16x32_bf16 v[132:135], v[156:159], v[182:185], 0
	v_mfma_f32_16x16x32_bf16 v[128:131], v[174:177], v[182:185], 0
	v_mfma_f32_16x16x32_bf16 v[116:119], v[156:159], v[192:195], 0
	v_mfma_f32_16x16x32_bf16 v[112:115], v[174:177], v[192:195], 0
	v_mfma_f32_16x16x32_bf16 v[100:103], v[156:159], v[200:203], 0
	v_mfma_f32_16x16x32_bf16 v[88:91], v[174:177], v[200:203], 0
	v_mfma_f32_16x16x32_bf16 v[68:71], v[156:159], v[208:211], 0
	v_mfma_f32_16x16x32_bf16 v[64:67], v[174:177], v[208:211], 0
	v_mfma_f32_16x16x32_bf16 v[132:135], v[160:163], v[188:191], v[132:135]
	v_mfma_f32_16x16x32_bf16 v[128:131], v[178:181], v[188:191], v[128:131]
	v_mfma_f32_16x16x32_bf16 v[116:119], v[160:163], v[196:199], v[116:119]
	v_mfma_f32_16x16x32_bf16 v[112:115], v[178:181], v[196:199], v[112:115]
	v_mfma_f32_16x16x32_bf16 v[100:103], v[160:163], v[204:207], v[100:103]
	v_mfma_f32_16x16x32_bf16 v[88:91], v[178:181], v[204:207], v[88:91]
	v_mfma_f32_16x16x32_bf16 v[68:71], v[160:163], v[212:215], v[68:71]
	v_mfma_f32_16x16x32_bf16 v[64:67], v[178:181], v[212:215], v[64:67]
	s_barrier
	s_setprio 0
	s_add_i32 s59, s53, s33
	v_lshl_add_u64 v[164:165], s[40:41], 0, v[144:145]
	s_mov_b32 m0, s59
	ds_read_b128 v[182:185], v171 offset:16384
	ds_read_b128 v[188:191], v171 offset:17408
	ds_read_b128 v[192:195], v171 offset:18432
	ds_read_b128 v[196:199], v171 offset:19456
	ds_read_b128 v[200:203], v171 offset:20480
	ds_read_b128 v[204:207], v171 offset:21504
	ds_read_b128 v[208:211], v171 offset:22528
	ds_read_b128 v[212:215], v171 offset:23552
	global_load_lds_dwordx4 v[164:165], off
	s_add_i32 m0, s59, 0x2000
	s_add_u32 s60, s40, 0x80000
	v_lshl_add_u64 v[216:217], s[40:41], 0, v[146:147]
	s_addc_u32 s61, s41, 0
	s_add_i32 s59, s54, s33
	global_load_lds_dwordx4 v[216:217], off
	v_lshl_add_u64 v[218:219], s[60:61], 0, v[144:145]
	s_mov_b32 m0, s59
	v_lshl_add_u64 v[220:221], s[42:43], 0, v[146:147]
	global_load_lds_dwordx4 v[218:219], off
	v_lshl_add_u64 v[218:219], s[60:61], 0, v[146:147]
	s_add_i32 m0, s59, 0x2000
	s_nop 0
	global_load_lds_dwordx4 v[218:219], off
	v_lshl_add_u64 v[218:219], s[42:43], 0, v[144:145]
	s_mov_b32 m0, s37
	s_nop 0
	global_load_lds_dwordx4 v[218:219], off
	s_mov_b32 m0, s44
	s_nop 0
	global_load_lds_dwordx4 v[220:221], off
	s_setprio 1
	s_waitcnt vmcnt(9)
	s_waitcnt lgkmcnt(0)
	s_barrier
; #define PG8_STAGE(bufoff, gbase, voff) do { _Pragma("unroll") for (int _i = 0; _i < 2; ++_i) \
;         __builtin_amdgcn_global_load_lds((const unsigned*)((const char*)(gbase) + (voff)[_i]), (PG8_LAS unsigned*)(lds + (bufoff) + ldsw + _i * 8192), 16, 0, 0); } while (0)
; #define PG8_LDA(dst, b, h) do { _Pragma("unroll") for (int m = 0; m < 4; ++m) _Pragma("unroll") for (int k = 0; k < 2; ++k) dst[m][k] = *(const PG8_LAS bf16x8*)(lds + PG8_SA(b, h) + aoff + m * 2048 + k * 1024); } while (0)
; #define PG8_LDB(dst, b, h) do { _Pragma("unroll") for (int n = 0; n < 2; ++n) _Pragma("unroll") for (int k = 0; k < 2; ++k) dst[n][k] = *(const PG8_LAS bf16x8*)(lds + PG8_SB(b, h) + boff + n * 2048 + k * 1024); } while (0)
; #define PG8_MMA(ai, bj, At, Bt) do { __builtin_amdgcn_s_setprio(1); _Pragma("unroll") for (int m = 0; m < 4; ++m) _Pragma("unroll") for (int n = 0; n < 2; ++n) _Pragma("unroll") for (int k = 0; k < 2; ++k) \
;         acc[ai][bj][m][n] = __builtin_amdgcn_mfma_f32_16x16x32_bf16(Bt[n][k], At[m][k], acc[ai][bj][m][n], 0, 0, 0); __builtin_amdgcn_s_setprio(0); } while (0)
; #define PG8_WAIT_V(n) asm volatile("s_waitcnt vmcnt(" #n ")" ::: "memory")
; template <class Epi, class Sched, bool ALIGN_EPI = false, bool SP2 = false>
; __device__ __forceinline__ void gemm_phase(PG8_LAS unsigned char* lds, const Gemm g, const Sched& S, const Epi& E) {
;     ...
;             PG8_LDB(B0, 0, 0); PG8_LDB(B1, 0, 1); PG8_SCHED; PG8_LDA(At, 0, 0); PG8_STAGE(PG8_SA(1, 1), a1 + hstep, voffA);
;             PG8_WAIT_V(8); PG8_WAIT_L(0); PG8_BAR; PG8_MMA(0, 0, At, B0); PG8_MMA(0, 1, At, B1); PG8_BAR; PG8_SCHED;
;             PG8_LDA(At, 0, 1); PG8_STAGE(PG8_SB(0, 0), b2, voffB); PG8_STAGE(PG8_SB(0, 1), b2 + hstep, voffB); PG8_STAGE(PG8_SA(0, 0), a2, voffA);
;             PG8_WAIT_V(8); PG8_WAIT_L(0); PG8_BAR; PG8_MMA(1, 0, At, B0); PG8_MMA(1, 1, At, B1); PG8_BAR; PG8_SCHED;
;             PG8_LDB(B0, 1, 0); PG8_LDB(B1, 1, 1); PG8_SCHED; PG8_LDA(At, 1, 0); PG8_STAGE(PG8_SA(0, 1), a2 + hstep, voffA);
;             PG8_WAIT_V(8); PG8_WAIT_L(0); PG8_BAR; PG8_MMA(0, 0, At, B0); PG8_MMA(0, 1, At, B1); PG8_BAR; PG8_SCHED;
;             PG8_LDA(At, 1, 1); PG8_STAGE(PG8_SB(1, 0), b3, voffB); PG8_STAGE(PG8_SB(1, 1), b3 + hstep, voffB); PG8_STAGE(PG8_SA(1, 0), a3, voffA);
;             PG8_WAIT_V(8); PG8_WAIT_L(0); PG8_BAR; PG8_MMA(1, 0, At, B0); PG8_MMA(1, 1, At, B1); PG8_BAR; PG8_SCHED;
	v_mfma_f32_16x16x32_bf16 v[60:63], v[72:75], v[182:185], 0
	v_mfma_f32_16x16x32_bf16 v[56:59], v[92:95], v[182:185], 0
	v_mfma_f32_16x16x32_bf16 v[44:47], v[72:75], v[192:195], 0
	v_mfma_f32_16x16x32_bf16 v[40:43], v[92:95], v[192:195], 0
	v_mfma_f32_16x16x32_bf16 v[28:31], v[72:75], v[200:203], 0
	v_mfma_f32_16x16x32_bf16 v[24:27], v[92:95], v[200:203], 0
	v_mfma_f32_16x16x32_bf16 v[12:15], v[72:75], v[208:211], 0
	v_mfma_f32_16x16x32_bf16 v[8:11], v[92:95], v[208:211], 0
	v_mfma_f32_16x16x32_bf16 v[60:63], v[84:87], v[188:191], v[60:63]
	v_mfma_f32_16x16x32_bf16 v[56:59], v[96:99], v[188:191], v[56:59]
	v_mfma_f32_16x16x32_bf16 v[44:47], v[84:87], v[196:199], v[44:47]
	v_mfma_f32_16x16x32_bf16 v[40:43], v[96:99], v[196:199], v[40:43]
	v_mfma_f32_16x16x32_bf16 v[28:31], v[84:87], v[204:207], v[28:31]
	v_mfma_f32_16x16x32_bf16 v[24:27], v[96:99], v[204:207], v[24:27]
	v_mfma_f32_16x16x32_bf16 v[12:15], v[84:87], v[212:215], v[12:15]
	v_mfma_f32_16x16x32_bf16 v[8:11], v[96:99], v[212:215], v[8:11]
	s_setprio 0
	s_setprio 1
	v_mfma_f32_16x16x32_bf16 v[52:55], v[156:159], v[182:185], 0
	v_mfma_f32_16x16x32_bf16 v[48:51], v[174:177], v[182:185], 0
	v_mfma_f32_16x16x32_bf16 v[36:39], v[156:159], v[192:195], 0
	v_mfma_f32_16x16x32_bf16 v[32:35], v[174:177], v[192:195], 0
	v_mfma_f32_16x16x32_bf16 v[20:23], v[156:159], v[200:203], 0
	v_mfma_f32_16x16x32_bf16 v[16:19], v[174:177], v[200:203], 0
	v_mfma_f32_16x16x32_bf16 v[4:7], v[156:159], v[208:211], 0
	v_mfma_f32_16x16x32_bf16 v[0:3], v[174:177], v[208:211], 0
	v_mfma_f32_16x16x32_bf16 v[52:55], v[160:163], v[188:191], v[52:55]
	v_mfma_f32_16x16x32_bf16 v[48:51], v[178:181], v[188:191], v[48:51]
	v_mfma_f32_16x16x32_bf16 v[36:39], v[160:163], v[196:199], v[36:39]
	v_mfma_f32_16x16x32_bf16 v[32:35], v[178:181], v[196:199], v[32:35]
	v_mfma_f32_16x16x32_bf16 v[20:23], v[160:163], v[204:207], v[20:23]
	v_mfma_f32_16x16x32_bf16 v[16:19], v[178:181], v[204:207], v[16:19]
	v_mfma_f32_16x16x32_bf16 v[4:7], v[160:163], v[212:215], v[4:7]
	v_mfma_f32_16x16x32_bf16 v[0:3], v[178:181], v[212:215], v[0:3]
	s_barrier
	s_setprio 0
	s_mov_b32 m0, s100
	s_nop 0
	global_load_lds_dwordx4 v[240:241], off
	v_lshl_add_u64 v[240:241], v[240:241], 0, s[98:99]
	s_add_i32 s59, 0, 0x18000
	s_add_i32 s60, 0, 0x1c000
	v_add_u32_e32 v96, s59, v167
	v_add_u32_e32 v173, s60, v167
	ds_read_b128 v[72:75], v96
	ds_read_b128 v[84:87], v96 offset:1024
	ds_read_b128 v[92:95], v96 offset:2048
	ds_read_b128 v[96:99], v96 offset:3072
	ds_read_b128 v[156:159], v173
	ds_read_b128 v[160:163], v173 offset:1024
	ds_read_b128 v[174:177], v173 offset:2048
	ds_read_b128 v[178:181], v173 offset:3072
	s_add_u32 s42, s42, 0x80000
	s_addc_u32 s43, s43, 0
	s_mov_b32 m0, s45
	v_lshl_add_u64 v[222:223], s[42:43], 0, v[144:145]
	ds_read_b128 v[182:185], v171 offset:32768
	ds_read_b128 v[188:191], v171 offset:33792
	ds_read_b128 v[192:195], v171 offset:34816
	ds_read_b128 v[196:199], v171 offset:35840
	ds_read_b128 v[200:203], v171 offset:36864
	ds_read_b128 v[204:207], v171 offset:37888
	ds_read_b128 v[208:211], v171 offset:38912
	ds_read_b128 v[212:215], v171 offset:39936
	global_load_lds_dwordx4 v[222:223], off
	v_lshl_add_u64 v[222:223], s[42:43], 0, v[146:147]
	s_mov_b32 m0, s46
	s_nop 0
	global_load_lds_dwordx4 v[222:223], off
	s_setprio 1
	s_waitcnt vmcnt(9)
	s_waitcnt lgkmcnt(0)
	s_barrier
	v_mfma_f32_16x16x32_bf16 v[140:143], v[72:75], v[182:185], v[140:143]
	v_mfma_f32_16x16x32_bf16 v[136:139], v[92:95], v[182:185], v[136:139]
	v_mfma_f32_16x16x32_bf16 v[124:127], v[72:75], v[192:195], v[124:127]
	v_mfma_f32_16x16x32_bf16 v[120:123], v[92:95], v[192:195], v[120:123]
	v_mfma_f32_16x16x32_bf16 v[108:111], v[72:75], v[200:203], v[108:111]
	v_mfma_f32_16x16x32_bf16 v[104:107], v[92:95], v[200:203], v[104:107]
	v_mfma_f32_16x16x32_bf16 v[80:83], v[72:75], v[208:211], v[80:83]
	v_mfma_f32_16x16x32_bf16 v[76:79], v[92:95], v[208:211], v[76:79]
	v_mfma_f32_16x16x32_bf16 v[140:143], v[84:87], v[188:191], v[140:143]
	v_mfma_f32_16x16x32_bf16 v[136:139], v[96:99], v[188:191], v[136:139]
	v_mfma_f32_16x16x32_bf16 v[124:127], v[84:87], v[196:199], v[124:127]
	v_mfma_f32_16x16x32_bf16 v[120:123], v[96:99], v[196:199], v[120:123]
	v_mfma_f32_16x16x32_bf16 v[108:111], v[84:87], v[204:207], v[108:111]
	v_mfma_f32_16x16x32_bf16 v[104:107], v[96:99], v[204:207], v[104:107]
	v_mfma_f32_16x16x32_bf16 v[80:83], v[84:87], v[212:215], v[80:83]
	v_mfma_f32_16x16x32_bf16 v[76:79], v[96:99], v[212:215], v[76:79]
	s_setprio 0
	s_setprio 1
	v_mfma_f32_16x16x32_bf16 v[132:135], v[156:159], v[182:185], v[132:135]
	v_mfma_f32_16x16x32_bf16 v[128:131], v[174:177], v[182:185], v[128:131]
	v_mfma_f32_16x16x32_bf16 v[116:119], v[156:159], v[192:195], v[116:119]
	v_mfma_f32_16x16x32_bf16 v[112:115], v[174:177], v[192:195], v[112:115]
	v_mfma_f32_16x16x32_bf16 v[100:103], v[156:159], v[200:203], v[100:103]
	v_mfma_f32_16x16x32_bf16 v[88:91], v[174:177], v[200:203], v[88:91]
	v_mfma_f32_16x16x32_bf16 v[68:71], v[156:159], v[208:211], v[68:71]
	v_mfma_f32_16x16x32_bf16 v[64:67], v[174:177], v[208:211], v[64:67]
	v_mfma_f32_16x16x32_bf16 v[132:135], v[160:163], v[188:191], v[132:135]
	v_mfma_f32_16x16x32_bf16 v[128:131], v[178:181], v[188:191], v[128:131]
	v_mfma_f32_16x16x32_bf16 v[116:119], v[160:163], v[196:199], v[116:119]
	v_mfma_f32_16x16x32_bf16 v[112:115], v[178:181], v[196:199], v[112:115]
	v_mfma_f32_16x16x32_bf16 v[100:103], v[160:163], v[204:207], v[100:103]
	v_mfma_f32_16x16x32_bf16 v[88:91], v[178:181], v[204:207], v[88:91]
	v_mfma_f32_16x16x32_bf16 v[68:71], v[160:163], v[212:215], v[68:71]
	v_mfma_f32_16x16x32_bf16 v[64:67], v[178:181], v[212:215], v[64:67]
	s_barrier
; #define PG8_STAGE(bufoff, gbase, voff) do { _Pragma("unroll") for (int _i = 0; _i < 2; ++_i) \
;         __builtin_amdgcn_global_load_lds((const unsigned*)((const char*)(gbase) + (voff)[_i]), (PG8_LAS unsigned*)(lds + (bufoff) + ldsw + _i * 8192), 16, 0, 0); } while (0)
; #define PG8_LDA(dst, b, h) do { _Pragma("unroll") for (int m = 0; m < 4; ++m) _Pragma("unroll") for (int k = 0; k < 2; ++k) dst[m][k] = *(const PG8_LAS bf16x8*)(lds + PG8_SA(b, h) + aoff + m * 2048 + k * 1024); } while (0)
; #define PG8_LDB(dst, b, h) do { _Pragma("unroll") for (int n = 0; n < 2; ++n) _Pragma("unroll") for (int k = 0; k < 2; ++k) dst[n][k] = *(const PG8_LAS bf16x8*)(lds + PG8_SB(b, h) + boff + n * 2048 + k * 1024); } while (0)
; #define PG8_MMA(ai, bj, At, Bt) do { __builtin_amdgcn_s_setprio(1); _Pragma("unroll") for (int m = 0; m < 4; ++m) _Pragma("unroll") for (int n = 0; n < 2; ++n) _Pragma("unroll") for (int k = 0; k < 2; ++k) \
;         acc[ai][bj][m][n] = __builtin_amdgcn_mfma_f32_16x16x32_bf16(Bt[n][k], At[m][k], acc[ai][bj][m][n], 0, 0, 0); __builtin_amdgcn_s_setprio(0); } while (0)
; #define PG8_WAIT_V(n) asm volatile("s_waitcnt vmcnt(" #n ")" ::: "memory")
; template <class Epi, class Sched, bool ALIGN_EPI = false, bool SP2 = false>
; __device__ __forceinline__ void gemm_phase(PG8_LAS unsigned char* lds, const Gemm g, const Sched& S, const Epi& E) {
;     ...
;             PG8_LDB(B0, 0, 0); PG8_LDB(B1, 0, 1); PG8_SCHED; PG8_LDA(At, 0, 0); PG8_STAGE(PG8_SA(1, 1), a1 + hstep, voffA);
;             PG8_WAIT_V(8); PG8_WAIT_L(0); PG8_BAR; PG8_MMA(0, 0, At, B0); PG8_MMA(0, 1, At, B1); PG8_BAR; PG8_SCHED;
;             PG8_LDA(At, 0, 1); PG8_STAGE(PG8_SB(0, 0), b2, voffB); PG8_STAGE(PG8_SB(0, 1), b2 + hstep, voffB); PG8_STAGE(PG8_SA(0, 0), a2, voffA);
;             PG8_WAIT_V(8); PG8_WAIT_L(0); PG8_BAR; PG8_MMA(1, 0, At, B0); PG8_MMA(1, 1, At, B1); PG8_BAR; PG8_SCHED;
;             PG8_LDB(B0, 1, 0); PG8_LDB(B1, 1, 1); PG8_SCHED; PG8_LDA(At, 1, 0); PG8_STAGE(PG8_SA(0, 1), a2 + hstep, voffA);
;             PG8_WAIT_V(8); PG8_WAIT_L(0); PG8_BAR; PG8_MMA(0, 0, At, B0); PG8_MMA(0, 1, At, B1); PG8_BAR; PG8_SCHED;
;             PG8_LDA(At, 1, 1); PG8_STAGE(PG8_SB(1, 0), b3, voffB); PG8_STAGE(PG8_SB(1, 1), b3 + hstep, voffB); PG8_STAGE(PG8_SA(1, 0), a3, voffA);
;             PG8_WAIT_V(8); PG8_WAIT_L(0); PG8_BAR; PG8_MMA(1, 0, At, B0); PG8_MMA(1, 1, At, B1); PG8_BAR; PG8_SCHED;
	s_setprio 0
	s_add_i32 s42, s59, s33
	v_lshl_add_u64 v[164:165], v[164:165], 0, s[12:13]
	s_mov_b32 m0, s42
	ds_read_b128 v[182:185], v171 offset:49152
	ds_read_b128 v[188:191], v171 offset:50176
	ds_read_b128 v[192:195], v171 offset:51200
	ds_read_b128 v[196:199], v171 offset:52224
	ds_read_b128 v[200:203], v171 offset:53248
	ds_read_b128 v[204:207], v171 offset:54272
	ds_read_b128 v[208:211], v171 offset:55296
	ds_read_b128 v[212:215], v171 offset:56320
	global_load_lds_dwordx4 v[164:165], off
	s_add_i32 m0, s42, 0x2000
	s_add_u32 s40, s40, 0x80080
	v_lshl_add_u64 v[164:165], v[216:217], 0, s[12:13]
	s_addc_u32 s41, s41, 0
	s_add_i32 s42, s60, s33
	global_load_lds_dwordx4 v[164:165], off
	v_lshl_add_u64 v[164:165], s[40:41], 0, v[144:145]
	s_mov_b32 m0, s42
	s_nop 0
	global_load_lds_dwordx4 v[164:165], off
	v_lshl_add_u64 v[164:165], s[40:41], 0, v[146:147]
	s_add_i32 m0, s42, 0x2000
	s_nop 0
	global_load_lds_dwordx4 v[164:165], off
	v_lshl_add_u64 v[164:165], v[218:219], 0, s[12:13]
	s_mov_b32 m0, s50
	s_nop 0
	global_load_lds_dwordx4 v[164:165], off
	v_lshl_add_u64 v[164:165], v[220:221], 0, s[12:13]
	s_mov_b32 m0, s51
	s_nop 0
	global_load_lds_dwordx4 v[164:165], off
	s_setprio 1
	s_waitcnt vmcnt(9)
	s_waitcnt lgkmcnt(0)
	s_barrier
	v_mfma_f32_16x16x32_bf16 v[60:63], v[72:75], v[182:185], v[60:63]
	v_mfma_f32_16x16x32_bf16 v[56:59], v[92:95], v[182:185], v[56:59]
	v_mfma_f32_16x16x32_bf16 v[44:47], v[72:75], v[192:195], v[44:47]
	v_mfma_f32_16x16x32_bf16 v[40:43], v[92:95], v[192:195], v[40:43]
	v_mfma_f32_16x16x32_bf16 v[28:31], v[72:75], v[200:203], v[28:31]
	v_mfma_f32_16x16x32_bf16 v[24:27], v[92:95], v[200:203], v[24:27]
	v_mfma_f32_16x16x32_bf16 v[12:15], v[72:75], v[208:211], v[12:15]
	v_mfma_f32_16x16x32_bf16 v[8:11], v[92:95], v[208:211], v[8:11]
	v_mfma_f32_16x16x32_bf16 v[60:63], v[84:87], v[188:191], v[60:63]
	v_mfma_f32_16x16x32_bf16 v[56:59], v[96:99], v[188:191], v[56:59]
	v_mfma_f32_16x16x32_bf16 v[44:47], v[84:87], v[196:199], v[44:47]
	v_mfma_f32_16x16x32_bf16 v[40:43], v[96:99], v[196:199], v[40:43]
	v_mfma_f32_16x16x32_bf16 v[28:31], v[84:87], v[204:207], v[28:31]
	v_mfma_f32_16x16x32_bf16 v[24:27], v[96:99], v[204:207], v[24:27]
	v_mfma_f32_16x16x32_bf16 v[12:15], v[84:87], v[212:215], v[12:15]
	v_mfma_f32_16x16x32_bf16 v[8:11], v[96:99], v[212:215], v[8:11]
	s_setprio 0
	s_setprio 1
	v_mfma_f32_16x16x32_bf16 v[52:55], v[156:159], v[182:185], v[52:55]
	v_mfma_f32_16x16x32_bf16 v[48:51], v[174:177], v[182:185], v[48:51]
	v_mfma_f32_16x16x32_bf16 v[36:39], v[156:159], v[192:195], v[36:39]
	v_mfma_f32_16x16x32_bf16 v[32:35], v[174:177], v[192:195], v[32:35]
	v_mfma_f32_16x16x32_bf16 v[20:23], v[156:159], v[200:203], v[20:23]
	v_mfma_f32_16x16x32_bf16 v[16:19], v[174:177], v[200:203], v[16:19]
	v_mfma_f32_16x16x32_bf16 v[4:7], v[156:159], v[208:211], v[4:7]
	v_mfma_f32_16x16x32_bf16 v[0:3], v[174:177], v[208:211], v[0:3]
	v_mfma_f32_16x16x32_bf16 v[52:55], v[160:163], v[188:191], v[52:55]
	v_mfma_f32_16x16x32_bf16 v[48:51], v[178:181], v[188:191], v[48:51]
	v_mfma_f32_16x16x32_bf16 v[36:39], v[160:163], v[196:199], v[36:39]
	v_mfma_f32_16x16x32_bf16 v[32:35], v[178:181], v[196:199], v[32:35]
	v_mfma_f32_16x16x32_bf16 v[20:23], v[160:163], v[204:207], v[20:23]
	v_mfma_f32_16x16x32_bf16 v[16:19], v[178:181], v[204:207], v[16:19]
	v_mfma_f32_16x16x32_bf16 v[4:7], v[160:163], v[212:215], v[4:7]
	v_mfma_f32_16x16x32_bf16 v[0:3], v[178:181], v[212:215], v[0:3]
	s_barrier
	s_setprio 0
	s_add_i32 s58, s58, 2
	s_add_u32 s38, s38, 0x100
	s_addc_u32 s39, s39, 0
	s_add_u32 s56, s56, 0x100
	s_addc_u32 s57, s57, 0
	s_cmp_gt_u32 s58, 29
.LBB0_894:
	s_mov_b32 m0, s100
	s_nop 0
	global_load_lds_dwordx4 v[240:241], off
	v_lshl_add_u64 v[240:241], v[240:241], 0, s[98:99]
	ds_read_b128 v[72:75], v169
	ds_read_b128 v[84:87], v169 offset:1024
	ds_read_b128 v[92:95], v169 offset:2048
	ds_read_b128 v[96:99], v169 offset:3072
	ds_read_b128 v[156:159], v170
	ds_read_b128 v[160:163], v170 offset:1024
	ds_read_b128 v[174:177], v170 offset:2048
	ds_read_b128 v[178:181], v170 offset:3072
	s_add_u32 s40, s38, 0xfff80080
	s_addc_u32 s41, s39, -1
	s_cmp_eq_u32 s58, 28
	s_cselect_b32 s43, s25, s41
	s_cselect_b32 s42, s35, s40
	s_cselect_b32 s41, s27, s57
	s_cselect_b32 s40, s55, s56
	v_lshl_add_u64 v[164:165], s[38:39], 0, v[148:149]
	s_add_i32 m0, s37, 0xc000
	ds_read_b128 v[182:185], v171
	ds_read_b128 v[188:191], v171 offset:1024
	ds_read_b128 v[192:195], v171 offset:2048
	ds_read_b128 v[196:199], v171 offset:3072
	ds_read_b128 v[200:203], v171 offset:4096
	ds_read_b128 v[204:207], v171 offset:5120
	ds_read_b128 v[208:211], v171 offset:6144
	ds_read_b128 v[212:215], v171 offset:7168
	global_load_lds_dwordx4 v[164:165], off
	v_lshl_add_u64 v[164:165], s[38:39], 0, v[150:151]
	s_add_i32 m0, s37, 0xe000
	s_nop 0
	global_load_lds_dwordx4 v[164:165], off
	s_setprio 1
	s_waitcnt vmcnt(9)
	s_waitcnt lgkmcnt(0)
	s_barrier
; #define PG8_STAGE(bufoff, gbase, voff) do { _Pragma("unroll") for (int _i = 0; _i < 2; ++_i) \
;         __builtin_amdgcn_global_load_lds((const unsigned*)((const char*)(gbase) + (voff)[_i]), (PG8_LAS unsigned*)(lds + (bufoff) + ldsw + _i * 8192), 16, 0, 0); } while (0)
; #define PG8_LDA(dst, b, h) do { _Pragma("unroll") for (int m = 0; m < 4; ++m) _Pragma("unroll") for (int k = 0; k < 2; ++k) dst[m][k] = *(const PG8_LAS bf16x8*)(lds + PG8_SA(b, h) + aoff + m * 2048 + k * 1024); } while (0)
; #define PG8_LDB(dst, b, h) do { _Pragma("unroll") for (int n = 0; n < 2; ++n) _Pragma("unroll") for (int k = 0; k < 2; ++k) dst[n][k] = *(const PG8_LAS bf16x8*)(lds + PG8_SB(b, h) + boff + n * 2048 + k * 1024); } while (0)
; #define PG8_MMA(ai, bj, At, Bt) do { __builtin_amdgcn_s_setprio(1); _Pragma("unroll") for (int m = 0; m < 4; ++m) _Pragma("unroll") for (int n = 0; n < 2; ++n) _Pragma("unroll") for (int k = 0; k < 2; ++k) \
;         acc[ai][bj][m][n] = __builtin_amdgcn_mfma_f32_16x16x32_bf16(Bt[n][k], At[m][k], acc[ai][bj][m][n], 0, 0, 0); __builtin_amdgcn_s_setprio(0); } while (0)
; #define PG8_WAIT_V(n) asm volatile("s_waitcnt vmcnt(" #n ")" ::: "memory")
; template <class Epi, class Sched, bool ALIGN_EPI = false, bool SP2 = false>
; __device__ __forceinline__ void gemm_phase(PG8_LAS unsigned char* lds, const Gemm g, const Sched& S, const Epi& E) {
;     ...
;             PG8_LDB(B0, 0, 0); PG8_LDB(B1, 0, 1); PG8_SCHED; PG8_LDA(At, 0, 0); PG8_STAGE(PG8_SA(1, 1), a1 + hstep, voffA);
;             PG8_WAIT_V(8); PG8_WAIT_L(0); PG8_BAR; PG8_MMA(0, 0, At, B0); PG8_MMA(0, 1, At, B1); PG8_BAR; PG8_SCHED;
;             PG8_LDA(At, 0, 1); PG8_STAGE(PG8_SB(0, 0), b2, voffB); PG8_STAGE(PG8_SB(0, 1), b2 + hstep, voffB); PG8_STAGE(PG8_SA(0, 0), a2, voffA);
;             PG8_WAIT_V(8); PG8_WAIT_L(0); PG8_BAR; PG8_MMA(1, 0, At, B0); PG8_MMA(1, 1, At, B1); PG8_BAR; PG8_SCHED;
;             PG8_LDB(B0, 1, 0); PG8_LDB(B1, 1, 1); PG8_SCHED; PG8_LDA(At, 1, 0); PG8_STAGE(PG8_SA(0, 1), a2 + hstep, voffA);
;             PG8_WAIT_V(8); PG8_WAIT_L(0); PG8_BAR; PG8_MMA(0, 0, At, B0); PG8_MMA(0, 1, At, B1); PG8_BAR; PG8_SCHED;
;             PG8_LDA(At, 1, 1); PG8_STAGE(PG8_SB(1, 0), b3, voffB); PG8_STAGE(PG8_SB(1, 1), b3 + hstep, voffB); PG8_STAGE(PG8_SA(1, 0), a3, voffA);
;             PG8_WAIT_V(8); PG8_WAIT_L(0); PG8_BAR; PG8_MMA(1, 0, At, B0); PG8_MMA(1, 1, At, B1); PG8_BAR; PG8_SCHED;
	v_mfma_f32_16x16x32_bf16 v[140:143], v[72:75], v[182:185], v[140:143]
	v_mfma_f32_16x16x32_bf16 v[136:139], v[92:95], v[182:185], v[136:139]
	v_mfma_f32_16x16x32_bf16 v[124:127], v[72:75], v[192:195], v[124:127]
	v_mfma_f32_16x16x32_bf16 v[120:123], v[92:95], v[192:195], v[120:123]
	v_mfma_f32_16x16x32_bf16 v[108:111], v[72:75], v[200:203], v[108:111]
	v_mfma_f32_16x16x32_bf16 v[104:107], v[92:95], v[200:203], v[104:107]
	v_mfma_f32_16x16x32_bf16 v[80:83], v[72:75], v[208:211], v[80:83]
	v_mfma_f32_16x16x32_bf16 v[76:79], v[92:95], v[208:211], v[76:79]
	v_mfma_f32_16x16x32_bf16 v[140:143], v[84:87], v[188:191], v[140:143]
	v_mfma_f32_16x16x32_bf16 v[136:139], v[96:99], v[188:191], v[136:139]
	v_mfma_f32_16x16x32_bf16 v[124:127], v[84:87], v[196:199], v[124:127]
	v_mfma_f32_16x16x32_bf16 v[120:123], v[96:99], v[196:199], v[120:123]
	v_mfma_f32_16x16x32_bf16 v[108:111], v[84:87], v[204:207], v[108:111]
	v_mfma_f32_16x16x32_bf16 v[104:107], v[96:99], v[204:207], v[104:107]
	v_mfma_f32_16x16x32_bf16 v[80:83], v[84:87], v[212:215], v[80:83]
	v_mfma_f32_16x16x32_bf16 v[76:79], v[96:99], v[212:215], v[76:79]
	s_setprio 0
	s_setprio 1
	v_mfma_f32_16x16x32_bf16 v[132:135], v[156:159], v[182:185], v[132:135]
	v_mfma_f32_16x16x32_bf16 v[128:131], v[174:177], v[182:185], v[128:131]
	v_mfma_f32_16x16x32_bf16 v[116:119], v[156:159], v[192:195], v[116:119]
	v_mfma_f32_16x16x32_bf16 v[112:115], v[174:177], v[192:195], v[112:115]
	v_mfma_f32_16x16x32_bf16 v[100:103], v[156:159], v[200:203], v[100:103]
	v_mfma_f32_16x16x32_bf16 v[88:91], v[174:177], v[200:203], v[88:91]
	v_mfma_f32_16x16x32_bf16 v[68:71], v[156:159], v[208:211], v[68:71]
	v_mfma_f32_16x16x32_bf16 v[64:67], v[174:177], v[208:211], v[64:67]
	v_mfma_f32_16x16x32_bf16 v[132:135], v[160:163], v[188:191], v[132:135]
	v_mfma_f32_16x16x32_bf16 v[128:131], v[178:181], v[188:191], v[128:131]
	v_mfma_f32_16x16x32_bf16 v[116:119], v[160:163], v[196:199], v[116:119]
	v_mfma_f32_16x16x32_bf16 v[112:115], v[178:181], v[196:199], v[112:115]
	v_mfma_f32_16x16x32_bf16 v[100:103], v[160:163], v[204:207], v[100:103]
	v_mfma_f32_16x16x32_bf16 v[88:91], v[178:181], v[204:207], v[88:91]
	v_mfma_f32_16x16x32_bf16 v[68:71], v[160:163], v[212:215], v[68:71]
	v_mfma_f32_16x16x32_bf16 v[64:67], v[178:181], v[212:215], v[64:67]
	s_barrier
	s_setprio 0
	s_add_i32 s59, s53, s33
	v_lshl_add_u64 v[164:165], s[40:41], 0, v[144:145]
	s_mov_b32 m0, s59
	ds_read_b128 v[182:185], v171 offset:16384
	ds_read_b128 v[188:191], v171 offset:17408
	ds_read_b128 v[192:195], v171 offset:18432
	ds_read_b128 v[196:199], v171 offset:19456
	ds_read_b128 v[200:203], v171 offset:20480
	ds_read_b128 v[204:207], v171 offset:21504
	ds_read_b128 v[208:211], v171 offset:22528
	ds_read_b128 v[212:215], v171 offset:23552
	global_load_lds_dwordx4 v[164:165], off
	s_add_i32 m0, s59, 0x2000
	s_add_u32 s60, s40, 0x80000
	v_lshl_add_u64 v[216:217], s[40:41], 0, v[146:147]
	s_addc_u32 s61, s41, 0
	s_add_i32 s59, s54, s33
	global_load_lds_dwordx4 v[216:217], off
	v_lshl_add_u64 v[218:219], s[60:61], 0, v[144:145]
	s_mov_b32 m0, s59
	v_lshl_add_u64 v[220:221], s[42:43], 0, v[146:147]
	global_load_lds_dwordx4 v[218:219], off
	v_lshl_add_u64 v[218:219], s[60:61], 0, v[146:147]
	s_add_i32 m0, s59, 0x2000
	s_nop 0
	global_load_lds_dwordx4 v[218:219], off
	v_lshl_add_u64 v[218:219], s[42:43], 0, v[144:145]
	s_mov_b32 m0, s37
	s_nop 0
	global_load_lds_dwordx4 v[218:219], off
	s_mov_b32 m0, s44
	s_nop 0
	global_load_lds_dwordx4 v[220:221], off
	s_setprio 1
	s_waitcnt vmcnt(9)
	s_waitcnt lgkmcnt(0)
	s_barrier
	v_mfma_f32_16x16x32_bf16 v[60:63], v[72:75], v[182:185], v[60:63]
	v_mfma_f32_16x16x32_bf16 v[56:59], v[92:95], v[182:185], v[56:59]
	v_mfma_f32_16x16x32_bf16 v[44:47], v[72:75], v[192:195], v[44:47]
	v_mfma_f32_16x16x32_bf16 v[40:43], v[92:95], v[192:195], v[40:43]
	v_mfma_f32_16x16x32_bf16 v[28:31], v[72:75], v[200:203], v[28:31]
	v_mfma_f32_16x16x32_bf16 v[24:27], v[92:95], v[200:203], v[24:27]
	v_mfma_f32_16x16x32_bf16 v[12:15], v[72:75], v[208:211], v[12:15]
	v_mfma_f32_16x16x32_bf16 v[8:11], v[92:95], v[208:211], v[8:11]
	v_mfma_f32_16x16x32_bf16 v[60:63], v[84:87], v[188:191], v[60:63]
	v_mfma_f32_16x16x32_bf16 v[56:59], v[96:99], v[188:191], v[56:59]
	v_mfma_f32_16x16x32_bf16 v[44:47], v[84:87], v[196:199], v[44:47]
	v_mfma_f32_16x16x32_bf16 v[40:43], v[96:99], v[196:199], v[40:43]
	v_mfma_f32_16x16x32_bf16 v[28:31], v[84:87], v[204:207], v[28:31]
	v_mfma_f32_16x16x32_bf16 v[24:27], v[96:99], v[204:207], v[24:27]
	v_mfma_f32_16x16x32_bf16 v[12:15], v[84:87], v[212:215], v[12:15]
	v_mfma_f32_16x16x32_bf16 v[8:11], v[96:99], v[212:215], v[8:11]
	s_setprio 0
	s_setprio 1
	v_mfma_f32_16x16x32_bf16 v[52:55], v[156:159], v[182:185], v[52:55]
	v_mfma_f32_16x16x32_bf16 v[48:51], v[174:177], v[182:185], v[48:51]
	v_mfma_f32_16x16x32_bf16 v[36:39], v[156:159], v[192:195], v[36:39]
	v_mfma_f32_16x16x32_bf16 v[32:35], v[174:177], v[192:195], v[32:35]
	v_mfma_f32_16x16x32_bf16 v[20:23], v[156:159], v[200:203], v[20:23]
	v_mfma_f32_16x16x32_bf16 v[16:19], v[174:177], v[200:203], v[16:19]
	v_mfma_f32_16x16x32_bf16 v[4:7], v[156:159], v[208:211], v[4:7]
	v_mfma_f32_16x16x32_bf16 v[0:3], v[174:177], v[208:211], v[0:3]
	v_mfma_f32_16x16x32_bf16 v[52:55], v[160:163], v[188:191], v[52:55]
	v_mfma_f32_16x16x32_bf16 v[48:51], v[178:181], v[188:191], v[48:51]
	v_mfma_f32_16x16x32_bf16 v[36:39], v[160:163], v[196:199], v[36:39]
	v_mfma_f32_16x16x32_bf16 v[32:35], v[178:181], v[196:199], v[32:35]
	v_mfma_f32_16x16x32_bf16 v[20:23], v[160:163], v[204:207], v[20:23]
	v_mfma_f32_16x16x32_bf16 v[16:19], v[178:181], v[204:207], v[16:19]
	v_mfma_f32_16x16x32_bf16 v[4:7], v[160:163], v[212:215], v[4:7]
	v_mfma_f32_16x16x32_bf16 v[0:3], v[178:181], v[212:215], v[0:3]
	s_barrier
; #define PG8_STAGE(bufoff, gbase, voff) do { _Pragma("unroll") for (int _i = 0; _i < 2; ++_i) \
;         __builtin_amdgcn_global_load_lds((const unsigned*)((const char*)(gbase) + (voff)[_i]), (PG8_LAS unsigned*)(lds + (bufoff) + ldsw + _i * 8192), 16, 0, 0); } while (0)
; #define PG8_LDA(dst, b, h) do { _Pragma("unroll") for (int m = 0; m < 4; ++m) _Pragma("unroll") for (int k = 0; k < 2; ++k) dst[m][k] = *(const PG8_LAS bf16x8*)(lds + PG8_SA(b, h) + aoff + m * 2048 + k * 1024); } while (0)
; #define PG8_LDB(dst, b, h) do { _Pragma("unroll") for (int n = 0; n < 2; ++n) _Pragma("unroll") for (int k = 0; k < 2; ++k) dst[n][k] = *(const PG8_LAS bf16x8*)(lds + PG8_SB(b, h) + boff + n * 2048 + k * 1024); } while (0)
; #define PG8_MMA(ai, bj, At, Bt) do { __builtin_amdgcn_s_setprio(1); _Pragma("unroll") for (int m = 0; m < 4; ++m) _Pragma("unroll") for (int n = 0; n < 2; ++n) _Pragma("unroll") for (int k = 0; k < 2; ++k) \
;         acc[ai][bj][m][n] = __builtin_amdgcn_mfma_f32_16x16x32_bf16(Bt[n][k], At[m][k], acc[ai][bj][m][n], 0, 0, 0); __builtin_amdgcn_s_setprio(0); } while (0)
; #define PG8_WAIT_V(n) asm volatile("s_waitcnt vmcnt(" #n ")" ::: "memory")
; template <class Epi, class Sched, bool ALIGN_EPI = false, bool SP2 = false>
; __device__ __forceinline__ void gemm_phase(PG8_LAS unsigned char* lds, const Gemm g, const Sched& S, const Epi& E) {
;     ...
;             PG8_LDB(B0, 0, 0); PG8_LDB(B1, 0, 1); PG8_SCHED; PG8_LDA(At, 0, 0); PG8_STAGE(PG8_SA(1, 1), a1 + hstep, voffA);
;             PG8_WAIT_V(8); PG8_WAIT_L(0); PG8_BAR; PG8_MMA(0, 0, At, B0); PG8_MMA(0, 1, At, B1); PG8_BAR; PG8_SCHED;
;             PG8_LDA(At, 0, 1); PG8_STAGE(PG8_SB(0, 0), b2, voffB); PG8_STAGE(PG8_SB(0, 1), b2 + hstep, voffB); PG8_STAGE(PG8_SA(0, 0), a2, voffA);
;             PG8_WAIT_V(8); PG8_WAIT_L(0); PG8_BAR; PG8_MMA(1, 0, At, B0); PG8_MMA(1, 1, At, B1); PG8_BAR; PG8_SCHED;
;             PG8_LDB(B0, 1, 0); PG8_LDB(B1, 1, 1); PG8_SCHED; PG8_LDA(At, 1, 0); PG8_STAGE(PG8_SA(0, 1), a2 + hstep, voffA);
;             PG8_WAIT_V(8); PG8_WAIT_L(0); PG8_BAR; PG8_MMA(0, 0, At, B0); PG8_MMA(0, 1, At, B1); PG8_BAR; PG8_SCHED;
;             PG8_LDA(At, 1, 1); PG8_STAGE(PG8_SB(1, 0), b3, voffB); PG8_STAGE(PG8_SB(1, 1), b3 + hstep, voffB); PG8_STAGE(PG8_SA(1, 0), a3, voffA);
;             PG8_WAIT_V(8); PG8_WAIT_L(0); PG8_BAR; PG8_MMA(1, 0, At, B0); PG8_MMA(1, 1, At, B1); PG8_BAR; PG8_SCHED;
	s_setprio 0
	s_mov_b32 m0, s100
	s_nop 0
	global_load_lds_dwordx4 v[240:241], off
	v_lshl_add_u64 v[240:241], v[240:241], 0, s[98:99]
	s_add_i32 s59, 0, 0x18000
	s_add_i32 s60, 0, 0x1c000
	v_add_u32_e32 v96, s59, v167
	v_add_u32_e32 v173, s60, v167
	ds_read_b128 v[72:75], v96
	ds_read_b128 v[84:87], v96 offset:1024
	ds_read_b128 v[92:95], v96 offset:2048
	ds_read_b128 v[96:99], v96 offset:3072
	ds_read_b128 v[156:159], v173
	ds_read_b128 v[160:163], v173 offset:1024
	ds_read_b128 v[174:177], v173 offset:2048
	ds_read_b128 v[178:181], v173 offset:3072
	s_add_u32 s42, s42, 0x80000
	s_addc_u32 s43, s43, 0
	s_mov_b32 m0, s45
	v_lshl_add_u64 v[222:223], s[42:43], 0, v[144:145]
	ds_read_b128 v[182:185], v171 offset:32768
	ds_read_b128 v[188:191], v171 offset:33792
	ds_read_b128 v[192:195], v171 offset:34816
	ds_read_b128 v[196:199], v171 offset:35840
	ds_read_b128 v[200:203], v171 offset:36864
	ds_read_b128 v[204:207], v171 offset:37888
	ds_read_b128 v[208:211], v171 offset:38912
	ds_read_b128 v[212:215], v171 offset:39936
	global_load_lds_dwordx4 v[222:223], off
	v_lshl_add_u64 v[222:223], s[42:43], 0, v[146:147]
	s_mov_b32 m0, s46
	s_nop 0
	global_load_lds_dwordx4 v[222:223], off
	s_setprio 1
	s_waitcnt vmcnt(9)
	s_waitcnt lgkmcnt(0)
	s_barrier
	v_mfma_f32_16x16x32_bf16 v[140:143], v[72:75], v[182:185], v[140:143]
	v_mfma_f32_16x16x32_bf16 v[136:139], v[92:95], v[182:185], v[136:139]
	v_mfma_f32_16x16x32_bf16 v[124:127], v[72:75], v[192:195], v[124:127]
	v_mfma_f32_16x16x32_bf16 v[120:123], v[92:95], v[192:195], v[120:123]
	v_mfma_f32_16x16x32_bf16 v[108:111], v[72:75], v[200:203], v[108:111]
	v_mfma_f32_16x16x32_bf16 v[104:107], v[92:95], v[200:203], v[104:107]
	v_mfma_f32_16x16x32_bf16 v[80:83], v[72:75], v[208:211], v[80:83]
	v_mfma_f32_16x16x32_bf16 v[76:79], v[92:95], v[208:211], v[76:79]
	v_mfma_f32_16x16x32_bf16 v[140:143], v[84:87], v[188:191], v[140:143]
	v_mfma_f32_16x16x32_bf16 v[136:139], v[96:99], v[188:191], v[136:139]
	v_mfma_f32_16x16x32_bf16 v[124:127], v[84:87], v[196:199], v[124:127]
	v_mfma_f32_16x16x32_bf16 v[120:123], v[96:99], v[196:199], v[120:123]
	v_mfma_f32_16x16x32_bf16 v[108:111], v[84:87], v[204:207], v[108:111]
	v_mfma_f32_16x16x32_bf16 v[104:107], v[96:99], v[204:207], v[104:107]
	v_mfma_f32_16x16x32_bf16 v[80:83], v[84:87], v[212:215], v[80:83]
	v_mfma_f32_16x16x32_bf16 v[76:79], v[96:99], v[212:215], v[76:79]
	s_setprio 0
	s_setprio 1
	v_mfma_f32_16x16x32_bf16 v[132:135], v[156:159], v[182:185], v[132:135]
	v_mfma_f32_16x16x32_bf16 v[128:131], v[174:177], v[182:185], v[128:131]
	v_mfma_f32_16x16x32_bf16 v[116:119], v[156:159], v[192:195], v[116:119]
	v_mfma_f32_16x16x32_bf16 v[112:115], v[174:177], v[192:195], v[112:115]
	v_mfma_f32_16x16x32_bf16 v[100:103], v[156:159], v[200:203], v[100:103]
	v_mfma_f32_16x16x32_bf16 v[88:91], v[174:177], v[200:203], v[88:91]
	v_mfma_f32_16x16x32_bf16 v[68:71], v[156:159], v[208:211], v[68:71]
	v_mfma_f32_16x16x32_bf16 v[64:67], v[174:177], v[208:211], v[64:67]
	v_mfma_f32_16x16x32_bf16 v[132:135], v[160:163], v[188:191], v[132:135]
	v_mfma_f32_16x16x32_bf16 v[128:131], v[178:181], v[188:191], v[128:131]
	v_mfma_f32_16x16x32_bf16 v[116:119], v[160:163], v[196:199], v[116:119]
	v_mfma_f32_16x16x32_bf16 v[112:115], v[178:181], v[196:199], v[112:115]
	v_mfma_f32_16x16x32_bf16 v[100:103], v[160:163], v[204:207], v[100:103]
	v_mfma_f32_16x16x32_bf16 v[88:91], v[178:181], v[204:207], v[88:91]
	v_mfma_f32_16x16x32_bf16 v[68:71], v[160:163], v[212:215], v[68:71]
	v_mfma_f32_16x16x32_bf16 v[64:67], v[178:181], v[212:215], v[64:67]
	s_barrier
; #define PG8_STAGE(bufoff, gbase, voff) do { _Pragma("unroll") for (int _i = 0; _i < 2; ++_i) \
;         __builtin_amdgcn_global_load_lds((const unsigned*)((const char*)(gbase) + (voff)[_i]), (PG8_LAS unsigned*)(lds + (bufoff) + ldsw + _i * 8192), 16, 0, 0); } while (0)
; #define PG8_LDA(dst, b, h) do { _Pragma("unroll") for (int m = 0; m < 4; ++m) _Pragma("unroll") for (int k = 0; k < 2; ++k) dst[m][k] = *(const PG8_LAS bf16x8*)(lds + PG8_SA(b, h) + aoff + m * 2048 + k * 1024); } while (0)
; #define PG8_LDB(dst, b, h) do { _Pragma("unroll") for (int n = 0; n < 2; ++n) _Pragma("unroll") for (int k = 0; k < 2; ++k) dst[n][k] = *(const PG8_LAS bf16x8*)(lds + PG8_SB(b, h) + boff + n * 2048 + k * 1024); } while (0)
; #define PG8_MMA(ai, bj, At, Bt) do { __builtin_amdgcn_s_setprio(1); _Pragma("unroll") for (int m = 0; m < 4; ++m) _Pragma("unroll") for (int n = 0; n < 2; ++n) _Pragma("unroll") for (int k = 0; k < 2; ++k) \
;         acc[ai][bj][m][n] = __builtin_amdgcn_mfma_f32_16x16x32_bf16(Bt[n][k], At[m][k], acc[ai][bj][m][n], 0, 0, 0); __builtin_amdgcn_s_setprio(0); } while (0)
; #define PG8_WAIT_V(n) asm volatile("s_waitcnt vmcnt(" #n ")" ::: "memory")
; template <class Epi, class Sched, bool ALIGN_EPI = false, bool SP2 = false>
; __device__ __forceinline__ void gemm_phase(PG8_LAS unsigned char* lds, const Gemm g, const Sched& S, const Epi& E) {
;     ...
;             PG8_LDB(B0, 0, 0); PG8_LDB(B1, 0, 1); PG8_SCHED; PG8_LDA(At, 0, 0); PG8_STAGE(PG8_SA(1, 1), a1 + hstep, voffA);
;             PG8_WAIT_V(8); PG8_WAIT_L(0); PG8_BAR; PG8_MMA(0, 0, At, B0); PG8_MMA(0, 1, At, B1); PG8_BAR; PG8_SCHED;
;             PG8_LDA(At, 0, 1); PG8_STAGE(PG8_SB(0, 0), b2, voffB); PG8_STAGE(PG8_SB(0, 1), b2 + hstep, voffB); PG8_STAGE(PG8_SA(0, 0), a2, voffA);
;             PG8_WAIT_V(8); PG8_WAIT_L(0); PG8_BAR; PG8_MMA(1, 0, At, B0); PG8_MMA(1, 1, At, B1); PG8_BAR; PG8_SCHED;
;             PG8_LDB(B0, 1, 0); PG8_LDB(B1, 1, 1); PG8_SCHED; PG8_LDA(At, 1, 0); PG8_STAGE(PG8_SA(0, 1), a2 + hstep, voffA);
;             PG8_WAIT_V(8); PG8_WAIT_L(0); PG8_BAR; PG8_MMA(0, 0, At, B0); PG8_MMA(0, 1, At, B1); PG8_BAR; PG8_SCHED;
;             PG8_LDA(At, 1, 1); PG8_STAGE(PG8_SB(1, 0), b3, voffB); PG8_STAGE(PG8_SB(1, 1), b3 + hstep, voffB); PG8_STAGE(PG8_SA(1, 0), a3, voffA);
;             PG8_WAIT_V(8); PG8_WAIT_L(0); PG8_BAR; PG8_MMA(1, 0, At, B0); PG8_MMA(1, 1, At, B1); PG8_BAR; PG8_SCHED;
	s_setprio 0
	s_add_i32 s42, s59, s33
	v_lshl_add_u64 v[164:165], v[164:165], 0, s[12:13]
	s_mov_b32 m0, s42
	ds_read_b128 v[182:185], v171 offset:49152
	ds_read_b128 v[188:191], v171 offset:50176
	ds_read_b128 v[192:195], v171 offset:51200
	ds_read_b128 v[196:199], v171 offset:52224
	ds_read_b128 v[200:203], v171 offset:53248
	ds_read_b128 v[204:207], v171 offset:54272
	ds_read_b128 v[208:211], v171 offset:55296
	ds_read_b128 v[212:215], v171 offset:56320
	global_load_lds_dwordx4 v[164:165], off
	s_add_i32 m0, s42, 0x2000
	s_add_u32 s40, s40, 0x80080
	v_lshl_add_u64 v[164:165], v[216:217], 0, s[12:13]
	s_addc_u32 s41, s41, 0
	s_add_i32 s42, s60, s33
	global_load_lds_dwordx4 v[164:165], off
	v_lshl_add_u64 v[164:165], s[40:41], 0, v[144:145]
	s_mov_b32 m0, s42
	s_nop 0
	global_load_lds_dwordx4 v[164:165], off
	v_lshl_add_u64 v[164:165], s[40:41], 0, v[146:147]
	s_add_i32 m0, s42, 0x2000
	s_nop 0
	global_load_lds_dwordx4 v[164:165], off
	v_lshl_add_u64 v[164:165], v[218:219], 0, s[12:13]
	s_mov_b32 m0, s50
	s_nop 0
	global_load_lds_dwordx4 v[164:165], off
	v_lshl_add_u64 v[164:165], v[220:221], 0, s[12:13]
	s_mov_b32 m0, s51
	s_nop 0
	global_load_lds_dwordx4 v[164:165], off
	s_setprio 1
	s_waitcnt vmcnt(9)
	s_waitcnt lgkmcnt(0)
	s_barrier
	v_mfma_f32_16x16x32_bf16 v[60:63], v[72:75], v[182:185], v[60:63]
	v_mfma_f32_16x16x32_bf16 v[56:59], v[92:95], v[182:185], v[56:59]
	v_mfma_f32_16x16x32_bf16 v[44:47], v[72:75], v[192:195], v[44:47]
	v_mfma_f32_16x16x32_bf16 v[40:43], v[92:95], v[192:195], v[40:43]
	v_mfma_f32_16x16x32_bf16 v[28:31], v[72:75], v[200:203], v[28:31]
	v_mfma_f32_16x16x32_bf16 v[24:27], v[92:95], v[200:203], v[24:27]
	v_mfma_f32_16x16x32_bf16 v[12:15], v[72:75], v[208:211], v[12:15]
	v_mfma_f32_16x16x32_bf16 v[8:11], v[92:95], v[208:211], v[8:11]
	v_mfma_f32_16x16x32_bf16 v[60:63], v[84:87], v[188:191], v[60:63]
	v_mfma_f32_16x16x32_bf16 v[56:59], v[96:99], v[188:191], v[56:59]
	v_mfma_f32_16x16x32_bf16 v[44:47], v[84:87], v[196:199], v[44:47]
	v_mfma_f32_16x16x32_bf16 v[40:43], v[96:99], v[196:199], v[40:43]
	v_mfma_f32_16x16x32_bf16 v[28:31], v[84:87], v[204:207], v[28:31]
	v_mfma_f32_16x16x32_bf16 v[24:27], v[96:99], v[204:207], v[24:27]
	v_mfma_f32_16x16x32_bf16 v[12:15], v[84:87], v[212:215], v[12:15]
	v_mfma_f32_16x16x32_bf16 v[8:11], v[96:99], v[212:215], v[8:11]
	s_setprio 0
	s_setprio 1
	v_mfma_f32_16x16x32_bf16 v[52:55], v[156:159], v[182:185], v[52:55]
	v_mfma_f32_16x16x32_bf16 v[48:51], v[174:177], v[182:185], v[48:51]
	v_mfma_f32_16x16x32_bf16 v[36:39], v[156:159], v[192:195], v[36:39]
	v_mfma_f32_16x16x32_bf16 v[32:35], v[174:177], v[192:195], v[32:35]
	v_mfma_f32_16x16x32_bf16 v[20:23], v[156:159], v[200:203], v[20:23]
	v_mfma_f32_16x16x32_bf16 v[16:19], v[174:177], v[200:203], v[16:19]
	v_mfma_f32_16x16x32_bf16 v[4:7], v[156:159], v[208:211], v[4:7]
	v_mfma_f32_16x16x32_bf16 v[0:3], v[174:177], v[208:211], v[0:3]
	v_mfma_f32_16x16x32_bf16 v[52:55], v[160:163], v[188:191], v[52:55]
	v_mfma_f32_16x16x32_bf16 v[48:51], v[178:181], v[188:191], v[48:51]
	v_mfma_f32_16x16x32_bf16 v[36:39], v[160:163], v[196:199], v[36:39]
	v_mfma_f32_16x16x32_bf16 v[32:35], v[178:181], v[196:199], v[32:35]
	v_mfma_f32_16x16x32_bf16 v[20:23], v[160:163], v[204:207], v[20:23]
	v_mfma_f32_16x16x32_bf16 v[16:19], v[178:181], v[204:207], v[16:19]
	v_mfma_f32_16x16x32_bf16 v[4:7], v[160:163], v[212:215], v[4:7]
	v_mfma_f32_16x16x32_bf16 v[0:3], v[178:181], v[212:215], v[0:3]
	s_barrier
	s_setprio 0
	s_add_i32 s58, s58, 2
	s_add_u32 s38, s38, 0x100
	s_addc_u32 s39, s39, 0
	s_add_u32 s56, s56, 0x100
	s_addc_u32 s57, s57, 0
	s_cmp_gt_u32 s58, 29
	s_cbranch_scc0 .LBB0_894
	s_and_b64 vcc, exec, s[14:15]
	s_cbranch_vccz .LBB0_897
	s_barrier

; __global__ void __launch_bounds__(NTHR, 2) fwd_megakernel(Args a) {
	.amdhsa_kernel _Z14fwd_megakernel4Args
		.amdhsa_group_segment_fixed_size 0
		.amdhsa_private_segment_fixed_size 0
		.amdhsa_kernarg_size 408
		.amdhsa_user_sgpr_count 2
		.amdhsa_user_sgpr_dispatch_ptr 0
		.amdhsa_user_sgpr_queue_ptr 0
		.amdhsa_user_sgpr_kernarg_segment_ptr 1
		.amdhsa_user_sgpr_dispatch_id 0
		.amdhsa_user_sgpr_kernarg_preload_length 0
		.amdhsa_user_sgpr_kernarg_preload_offset 0
		.amdhsa_user_sgpr_private_segment_size 0
		.amdhsa_uses_dynamic_stack 0
		.amdhsa_enable_private_segment 0
		.amdhsa_system_sgpr_workgroup_id_x 1
		.amdhsa_system_sgpr_workgroup_id_y 0
		.amdhsa_system_sgpr_workgroup_id_z 0
		.amdhsa_system_sgpr_workgroup_info 0
		.amdhsa_system_vgpr_workitem_id 2
		.amdhsa_next_free_vgpr 243
		.amdhsa_next_free_sgpr 102
		.amdhsa_accum_offset 244
		.amdhsa_reserve_vcc 1
		.amdhsa_float_round_mode_32 0
		.amdhsa_float_round_mode_16_64 0
		.amdhsa_float_denorm_mode_32 3
		.amdhsa_float_denorm_mode_16_64 3
		.amdhsa_dx10_clamp 1
		.amdhsa_ieee_mode 1
		.amdhsa_fp16_overflow 0
		.amdhsa_tg_split 0
		.amdhsa_exception_fp_ieee_invalid_op 0
		.amdhsa_exception_fp_denorm_src 0
		.amdhsa_exception_fp_ieee_div_zero 0
		.amdhsa_exception_fp_ieee_overflow 0
		.amdhsa_exception_fp_ieee_underflow 0
		.amdhsa_exception_fp_ieee_inexact 0
		.amdhsa_exception_int_div_zero 0
	.end_amdhsa_kernel

; __global__ void __launch_bounds__(NTHR, 2) fwd_megakernel(Args a) {
amdhsa.kernels:
  - .agpr_count:     0
    .args:
      - .offset:         0
        .size:           152
        .value_kind:     by_value
      - .offset:         152
        .size:           4
        .value_kind:     hidden_block_count_x
      - .offset:         156
        .size:           4
        .value_kind:     hidden_block_count_y
      - .offset:         160
        .size:           4
        .value_kind:     hidden_block_count_z
      - .offset:         164
        .size:           2
        .value_kind:     hidden_group_size_x
      - .offset:         166
        .size:           2
        .value_kind:     hidden_group_size_y
      - .offset:         168
        .size:           2
        .value_kind:     hidden_group_size_z
      - .offset:         170
        .size:           2
        .value_kind:     hidden_remainder_x
      - .offset:         172
        .size:           2
        .value_kind:     hidden_remainder_y
      - .offset:         174
        .size:           2
        .value_kind:     hidden_remainder_z
      - .offset:         192
        .size:           8
        .value_kind:     hidden_global_offset_x
      - .offset:         200
        .size:           8
        .value_kind:     hidden_global_offset_y
      - .offset:         208
        .size:           8
        .value_kind:     hidden_global_offset_z
      - .offset:         216
        .size:           2
        .value_kind:     hidden_grid_dims
      - .offset:         240
        .size:           8
        .value_kind:     hidden_multigrid_sync_arg
      - .offset:         272
        .size:           4
        .value_kind:     hidden_dynamic_lds_size
    .group_segment_fixed_size: 0
    .kernarg_segment_align: 8
    .kernarg_segment_size: 408
    .language:       OpenCL C
    .language_version:
      - 2
      - 0
    .max_flat_workgroup_size: 512
    .name:           _Z14fwd_megakernel4Args
    .private_segment_fixed_size: 0
    .sgpr_count:     108
    .sgpr_spill_count: 83
    .symbol:         _Z14fwd_megakernel4Args.kd
    .uniform_work_group_size: 1
    .uses_dynamic_stack: false
    .vgpr_count:     243
    .vgpr_spill_count: 0
    .wavefront_size: 64
